# attention: next q-block's Q row loads issued at the top of the current q-block epilogue (their registers are dead after the tile loop)
# speedup vs baseline: 1.0870x; 1.0024x over previous
.LBB0_44:
	s_cmp_eq_u32 s38, 0
	s_cbranch_scc1 .Lq_nopref
	s_add_i32 s53, s38, -1
	s_lshl_b32 s53, s53, 8
	s_add_i32 s53, s35, s53
	v_or_b32_e32 v108, s53, v184
	v_mov_b64_e32 v[110:111], s[50:51]
	v_lshlrev_b32_e32 v112, 3, v185
	v_mad_i64_i32 v[110:111], vcc, v108, s17, v[110:111]
	v_ashrrev_i32_e32 v113, 31, v112
	v_lshl_add_u64 v[110:111], v[112:113], 1, v[110:111]
	global_load_dwordx4 v[84:87], v[110:111], off offset:128
	global_load_dwordx4 v[88:91], v[110:111], off offset:160
	global_load_dwordx4 v[92:95], v[110:111], off offset:96
	global_load_dwordx4 v[118:121], v[110:111], off offset:64
	global_load_dwordx4 v[122:125], v[110:111], off offset:32
	global_load_dwordx4 v[126:129], v[110:111], off

.LBB0_51:
	s_or_b64 exec, exec, s[52:53]
	s_lshl_b32 s48, s38, 8
	s_add_i32 s52, s35, s48
	v_mov_b32_e32 v1, v185
	v_or_b32_e32 v6, s52, v184
	global_load_dwordx4 v[2:5], v[160:161], off
	v_mov_b64_e32 v[8:9], s[50:51]
	v_lshlrev_b32_e32 v18, 3, v1
	v_mad_i64_i32 v[8:9], s[48:49], v6, s17, v[8:9]
	v_ashrrev_i32_e32 v19, 31, v18
	v_lshl_add_u64 v[8:9], v[18:19], 1, v[8:9]
	s_cmp_lg_u32 s38, 7
	s_cbranch_scc1 .Lq_skipQ
	global_load_dwordx4 v[84:87], v[8:9], off offset:128
	global_load_dwordx4 v[88:91], v[8:9], off offset:160
	global_load_dwordx4 v[92:95], v[8:9], off offset:96
	global_load_dwordx4 v[118:121], v[8:9], off offset:64
	global_load_dwordx4 v[122:125], v[8:9], off offset:32
	global_load_dwordx4 v[126:129], v[8:9], off
.Lq_skipQ:
	v_ashrrev_i32_e32 v7, 31, v6
	v_lshlrev_b64 v[6:7], 6, v[6:7]
	v_lshlrev_b64 v[8:9], 2, v[18:19]
	v_lshl_add_u64 v[18:19], s[2:3], 0, v[6:7]
	v_lshl_add_u64 v[6:7], s[4:5], 0, v[6:7]
	v_lshl_add_u32 v1, v1, 5, 0
	v_lshl_add_u64 v[18:19], v[18:19], 0, v[8:9]
	v_lshl_add_u64 v[34:35], v[6:7], 0, v[8:9]
	ds_read_b128 v[70:73], v1 offset:46080
	ds_read_b128 v[62:65], v1 offset:46096
	ds_read_b128 v[58:61], v1 offset:46144
	ds_read_b128 v[54:57], v1 offset:46160
	ds_read_b128 v[50:53], v1 offset:46208
	ds_read_b128 v[46:49], v1 offset:46224
	ds_read_b128 v[42:45], v1 offset:46272
	ds_read_b128 v[38:41], v1 offset:46288
	ds_read_b128 v[30:33], v1 offset:46336
	ds_read_b128 v[14:17], v1 offset:46352
	ds_read_b128 v[22:25], v1 offset:46400
	ds_read_b128 v[10:13], v1 offset:46416
	global_load_dwordx4 v[6:9], v[18:19], off offset:16
	global_load_dwordx4 v[26:29], v[18:19], off
	s_nop 0
	global_load_dwordx4 v[18:21], v[34:35], off offset:16
	s_nop 0
	global_load_dwordx4 v[34:37], v[34:35], off
	s_waitcnt vmcnt(9)
	v_lshlrev_b32_e32 v74, 16, v87
	v_and_b32_e32 v75, 0xffff0000, v87
	v_lshlrev_b32_e32 v78, 16, v86
	v_and_b32_e32 v79, 0xffff0000, v86
	s_waitcnt vmcnt(7)
	v_lshlrev_b32_e32 v86, 16, v93
	v_and_b32_e32 v87, 0xffff0000, v93
	v_lshlrev_b32_e32 v112, 16, v92
	v_and_b32_e32 v113, 0xffff0000, v92
	s_waitcnt vmcnt(5)
	v_lshlrev_b32_e32 v92, 16, v125
	v_and_b32_e32 v93, 0xffff0000, v125
	s_waitcnt vmcnt(4)
	v_and_b32_e32 v125, 0xffff0000, v126
	v_lshlrev_b32_e32 v98, 16, v119
	v_and_b32_e32 v99, 0xffff0000, v119
	v_lshlrev_b32_e32 v116, 16, v118
	v_and_b32_e32 v117, 0xffff0000, v118
	v_lshlrev_b32_e32 v118, 16, v124
	v_and_b32_e32 v119, 0xffff0000, v124
	v_lshlrev_b32_e32 v124, 16, v126
	v_mul_f32_e32 v1, v125, v125
	v_lshlrev_b32_e32 v100, 16, v90
	v_and_b32_e32 v101, 0xffff0000, v90
	v_lshlrev_b32_e32 v90, 16, v127
	v_fmac_f32_e32 v1, v124, v124
	v_lshlrev_b32_e32 v76, 16, v91
	v_and_b32_e32 v77, 0xffff0000, v91
	v_and_b32_e32 v91, 0xffff0000, v127
	v_fmac_f32_e32 v1, v90, v90
	v_lshlrev_b32_e32 v96, 16, v121
	v_and_b32_e32 v97, 0xffff0000, v121
	v_lshlrev_b32_e32 v114, 16, v120
	v_and_b32_e32 v115, 0xffff0000, v120
	v_lshlrev_b32_e32 v120, 16, v122
	v_and_b32_e32 v121, 0xffff0000, v122
	v_lshlrev_b32_e32 v122, 16, v128
	v_fmac_f32_e32 v1, v91, v91
	v_lshlrev_b32_e32 v102, 16, v85
	v_and_b32_e32 v103, 0xffff0000, v85
	v_lshlrev_b32_e32 v106, 16, v84
	v_and_b32_e32 v107, 0xffff0000, v84
	v_lshlrev_b32_e32 v84, 16, v95
	v_and_b32_e32 v85, 0xffff0000, v95
	v_lshlrev_b32_e32 v110, 16, v94
	v_and_b32_e32 v111, 0xffff0000, v94
	v_lshlrev_b32_e32 v94, 16, v123
	v_and_b32_e32 v95, 0xffff0000, v123
	v_and_b32_e32 v123, 0xffff0000, v128
	v_fmac_f32_e32 v1, v122, v122
	v_lshlrev_b32_e32 v108, 16, v88
	v_and_b32_e32 v109, 0xffff0000, v88
	v_lshlrev_b32_e32 v88, 16, v129
	v_fmac_f32_e32 v1, v123, v123
	v_lshlrev_b32_e32 v104, 16, v89
	v_and_b32_e32 v105, 0xffff0000, v89
	v_and_b32_e32 v89, 0xffff0000, v129
	v_fmac_f32_e32 v1, v88, v88
	v_fmac_f32_e32 v1, v89, v89
	v_fmac_f32_e32 v1, v120, v120
	v_fmac_f32_e32 v1, v121, v121
	v_fmac_f32_e32 v1, v94, v94
	v_fmac_f32_e32 v1, v95, v95
	v_fmac_f32_e32 v1, v118, v118
	v_fmac_f32_e32 v1, v119, v119
	v_fmac_f32_e32 v1, v92, v92
	v_fmac_f32_e32 v1, v93, v93
	v_fmac_f32_e32 v1, v116, v116
	v_fmac_f32_e32 v1, v117, v117
	v_fmac_f32_e32 v1, v98, v98
	v_fmac_f32_e32 v1, v99, v99
	v_fmac_f32_e32 v1, v114, v114
	v_fmac_f32_e32 v1, v115, v115
	v_fmac_f32_e32 v1, v96, v96
	v_fmac_f32_e32 v1, v97, v97
	v_fmac_f32_e32 v1, v112, v112
	v_fmac_f32_e32 v1, v113, v113
	v_fmac_f32_e32 v1, v86, v86
	v_fmac_f32_e32 v1, v87, v87
	v_fmac_f32_e32 v1, v110, v110
	v_fmac_f32_e32 v1, v111, v111
	v_fmac_f32_e32 v1, v84, v84
	v_pk_mul_f32 v[210:211], v[106:107], v[106:107]
	v_fmac_f32_e32 v1, v85, v85
	v_add_f32_e32 v1, v1, v210
	v_pk_mul_f32 v[180:181], v[102:103], v[102:103]
	v_add_f32_e32 v1, v1, v211
	v_add_f32_e32 v1, v1, v180
	v_pk_mul_f32 v[176:177], v[78:79], v[78:79]
	v_add_f32_e32 v1, v1, v181
	v_add_f32_e32 v1, v1, v176
	v_pk_mul_f32 v[130:131], v[74:75], v[74:75]
	v_add_f32_e32 v1, v1, v177
	v_add_f32_e32 v1, v1, v130
	v_pk_mul_f32 v[212:213], v[108:109], v[108:109]
	v_add_f32_e32 v1, v1, v131
	v_add_f32_e32 v1, v1, v212
	v_pk_mul_f32 v[182:183], v[104:105], v[104:105]
	v_add_f32_e32 v1, v1, v213
	v_add_f32_e32 v1, v1, v182
	v_pk_mul_f32 v[178:179], v[100:101], v[100:101]
	v_add_f32_e32 v1, v1, v183
	v_add_f32_e32 v1, v1, v178
	v_pk_mul_f32 v[174:175], v[76:77], v[76:77]
	v_add_f32_e32 v1, v1, v179
	v_add_f32_e32 v1, v1, v174
	v_add_f32_e32 v1, v1, v175
	v_mov_b32_e32 v126, v1
	s_nop 1
	v_permlane32_swap_b32_e32 v1, v126
	v_add_u32_e32 v127, v186, v134
	ds_write_b128 v127, v[66:69]
	s_and_saveexec_b64 s[48:49], s[42:43]
	s_xor_b64 s[54:55], exec, s[48:49]
	s_cbranch_execz .LBB0_55
	s_and_saveexec_b64 s[56:57], s[44:45]
	s_cbranch_execz .LBB0_54
	v_add_f32_e32 v66, v153, v155
	v_fmamk_f32 v66, v66, 0x3c2aaaab, v207
	v_rsq_f32_e32 v66, v66
	v_add_u32_e32 v67, 0, v187
	ds_write_b32 v67, v66 offset:21504

.Latt2_exit:
	v_lshlrev_b32_e32 v1, 4, v164
	v_add_u32_e32 v1, 0x14000, v1
	ds_read_b128 v[194:197], v1
	ds_read_b128 v[198:201], v1 offset:8192
	ds_read_b128 v[202:205], v1 offset:16384
	s_waitcnt lgkmcnt(0)
	s_branch .LBB0_44
	s_nop 0
	s_nop 0
	s_nop 0
	s_nop 0
	s_nop 0
	s_nop 0
	s_nop 0
	s_nop 0
	s_nop 0
	s_nop 0
	s_nop 0
	s_nop 0
	s_nop 0
	s_nop 0
	s_nop 0
	s_nop 0
